# trailing half: offset-restoring barrier moved after its next-unit set-up and accumulator zeroing
# speedup vs baseline: 1.0249x; 1.0011x over previous
; #define PG8_BAR __builtin_amdgcn_s_barrier()
; template <class Epi, class Sched, bool ALIGN_EPI = false, bool SP2 = false>
; __device__ __forceinline__ void gemm_phase(PG8_LAS unsigned char* lds, const Gemm g, const Sched& S, const Epi& E, const int wid_) {
;     ...
; #pragma unroll
;         for (int a = 0; a < 2; ++a)
; #pragma unroll
;             for (int b = 0; b < 2; ++b)
; #pragma unroll
;                 for (int m = 0; m < 4; ++m)
; #pragma unroll
;                     for (int n = 0; n < 2; ++n) acc[a][b][m][n] = (f32x4){0.f, 0.f, 0.f, 0.f};
;         cur = nxt; cA = nA; cB = nB; ++ui;
;         if constexpr (ALIGN_EPI) { if (wr == 1) PG8_BAR; }
.Lprio_a:
	v_mov_b64_e32 v[0:1], 0
	v_mov_b64_e32 v[2:3], 0
	v_mov_b64_e32 v[4:5], 0
	v_mov_b64_e32 v[6:7], 0
	v_mov_b64_e32 v[8:9], 0
	v_mov_b64_e32 v[10:11], 0
	v_mov_b64_e32 v[12:13], 0
	v_mov_b64_e32 v[14:15], 0
	v_mov_b64_e32 v[16:17], 0
	v_mov_b64_e32 v[18:19], 0
	v_mov_b64_e32 v[20:21], 0
	v_mov_b64_e32 v[22:23], 0
	v_mov_b64_e32 v[24:25], 0
	v_mov_b64_e32 v[26:27], 0
	v_mov_b64_e32 v[28:29], 0
	v_mov_b64_e32 v[30:31], 0
	v_mov_b64_e32 v[32:33], 0
	v_mov_b64_e32 v[34:35], 0
	v_mov_b64_e32 v[36:37], 0
	v_mov_b64_e32 v[38:39], 0
	v_mov_b64_e32 v[40:41], 0
	v_mov_b64_e32 v[42:43], 0
	v_mov_b64_e32 v[44:45], 0
	v_mov_b64_e32 v[46:47], 0
	v_mov_b64_e32 v[48:49], 0
	v_mov_b64_e32 v[50:51], 0
	v_mov_b64_e32 v[52:53], 0
	v_mov_b64_e32 v[54:55], 0
	v_mov_b64_e32 v[56:57], 0
	v_mov_b64_e32 v[58:59], 0
	v_mov_b64_e32 v[60:61], 0
	v_mov_b64_e32 v[62:63], 0
	v_mov_b64_e32 v[64:65], 0
	v_mov_b64_e32 v[66:67], 0
	v_mov_b64_e32 v[68:69], 0
	v_mov_b64_e32 v[70:71], 0
	v_mov_b64_e32 v[72:73], 0
	v_mov_b64_e32 v[74:75], 0
	v_mov_b64_e32 v[76:77], 0
	v_mov_b64_e32 v[78:79], 0
	v_mov_b64_e32 v[80:81], 0
	v_mov_b64_e32 v[82:83], 0
	v_mov_b64_e32 v[84:85], 0
	v_mov_b64_e32 v[86:87], 0
	v_mov_b64_e32 v[88:89], 0
	v_mov_b64_e32 v[90:91], 0
	v_mov_b64_e32 v[92:93], 0
	v_mov_b64_e32 v[94:95], 0
	v_mov_b64_e32 v[96:97], 0
	v_mov_b64_e32 v[98:99], 0
	v_mov_b64_e32 v[100:101], 0
	v_mov_b64_e32 v[102:103], 0
	v_mov_b64_e32 v[104:105], 0
	v_mov_b64_e32 v[106:107], 0
	v_mov_b64_e32 v[108:109], 0
	v_mov_b64_e32 v[110:111], 0
	v_mov_b64_e32 v[112:113], 0
	v_mov_b64_e32 v[114:115], 0
	v_mov_b64_e32 v[116:117], 0
	v_mov_b64_e32 v[118:119], 0
	v_mov_b64_e32 v[120:121], 0
	v_mov_b64_e32 v[122:123], 0
	v_mov_b64_e32 v[124:125], 0
	v_mov_b64_e32 v[126:127], 0
	s_cmp_gt_u32 s96, 1
	s_cselect_b64 vcc, s[92:93], 0
	s_cbranch_vccz .Llate_bar_skip
	s_barrier
